# NSA top-k radix threshold search fully unrolled (no loop counter / branch SALU); on top of v53
# speedup vs baseline: 1.0067x; 1.0018x over previous
; __device__ __forceinline__ float rdlane(float v, int l) { return __int_as_float(__builtin_amdgcn_readlane(__float_as_int(v), l)); }
; __device__ __forceinline__ void nsa_unit(Frame& F, int b, int g, int c) {
;     ...
;         for (int tt = 0; tt < 8; ++tt) {
;             const int tl = 8 * w + tt; unsigned long long mk;
;             if (c >= 16) {
;                 const bool cand = (lane >= 1) && (lane <= c - 2);
;                 const float v = cand ? impG[tl * 64 + lane] + impL[tl * 64 + lane] : -__builtin_inff();
;                 int rank = 0;
;                 for (int i = 0; i < 64; ++i) { const float vi = rdlane(v, i); rank += ((vi > v) || (vi == v && i < lane)) ? 1 : 0; }
;                 mk = __ballot(cand && rank < 13) | 1ull | (1ull << c) | (1ull << (c - 1));
;             } else mk = (2ull << c) - 1ull;
;             if (lane == 0) selm[tl] = mk;
;             wuni |= mk;
.LBB0_869:
	s_or_b64 exec, exec, s[0:1]
	v_ashrrev_i32_e32 v3, 31, v2
	v_or_b32_e32 v3, 0x80000000, v3
	v_xor_b32_e32 v3, v2, v3
	s_mov_b32 s98, 0
	s_or_b32 s100, s98, 0x80000000
	v_cmp_le_u32_e32 vcc, s100, v3
	s_and_b64 s[0:1], vcc, s[8:9]
	s_bcnt1_i32_b64 s101, s[0:1]
	s_cmp_ge_u32 s101, 13
	s_cselect_b32 s98, s100, s98
	s_or_b32 s100, s98, 0x40000000
	v_cmp_le_u32_e32 vcc, s100, v3
	s_and_b64 s[0:1], vcc, s[8:9]
	s_bcnt1_i32_b64 s101, s[0:1]
	s_cmp_ge_u32 s101, 13
	s_cselect_b32 s98, s100, s98
	s_or_b32 s100, s98, 0x20000000
	v_cmp_le_u32_e32 vcc, s100, v3
	s_and_b64 s[0:1], vcc, s[8:9]
	s_bcnt1_i32_b64 s101, s[0:1]
	s_cmp_ge_u32 s101, 13
	s_cselect_b32 s98, s100, s98
	s_or_b32 s100, s98, 0x10000000
	v_cmp_le_u32_e32 vcc, s100, v3
	s_and_b64 s[0:1], vcc, s[8:9]
	s_bcnt1_i32_b64 s101, s[0:1]
	s_cmp_ge_u32 s101, 13
	s_cselect_b32 s98, s100, s98
	s_or_b32 s100, s98, 0x8000000
	v_cmp_le_u32_e32 vcc, s100, v3
	s_and_b64 s[0:1], vcc, s[8:9]
	s_bcnt1_i32_b64 s101, s[0:1]
	s_cmp_ge_u32 s101, 13
	s_cselect_b32 s98, s100, s98
	s_or_b32 s100, s98, 0x4000000
	v_cmp_le_u32_e32 vcc, s100, v3
	s_and_b64 s[0:1], vcc, s[8:9]
	s_bcnt1_i32_b64 s101, s[0:1]
	s_cmp_ge_u32 s101, 13
	s_cselect_b32 s98, s100, s98
	s_or_b32 s100, s98, 0x2000000
	v_cmp_le_u32_e32 vcc, s100, v3
	s_and_b64 s[0:1], vcc, s[8:9]
	s_bcnt1_i32_b64 s101, s[0:1]
	s_cmp_ge_u32 s101, 13
	s_cselect_b32 s98, s100, s98
	s_or_b32 s100, s98, 0x1000000
	v_cmp_le_u32_e32 vcc, s100, v3
	s_and_b64 s[0:1], vcc, s[8:9]
	s_bcnt1_i32_b64 s101, s[0:1]
	s_cmp_ge_u32 s101, 13
	s_cselect_b32 s98, s100, s98
	s_or_b32 s100, s98, 0x800000
	v_cmp_le_u32_e32 vcc, s100, v3
	s_and_b64 s[0:1], vcc, s[8:9]
	s_bcnt1_i32_b64 s101, s[0:1]
	s_cmp_ge_u32 s101, 13
	s_cselect_b32 s98, s100, s98
	s_or_b32 s100, s98, 0x400000
	v_cmp_le_u32_e32 vcc, s100, v3
	s_and_b64 s[0:1], vcc, s[8:9]
	s_bcnt1_i32_b64 s101, s[0:1]
	s_cmp_ge_u32 s101, 13
	s_cselect_b32 s98, s100, s98
	s_or_b32 s100, s98, 0x200000
	v_cmp_le_u32_e32 vcc, s100, v3
	s_and_b64 s[0:1], vcc, s[8:9]
	s_bcnt1_i32_b64 s101, s[0:1]
	s_cmp_ge_u32 s101, 13
	s_cselect_b32 s98, s100, s98
	s_or_b32 s100, s98, 0x100000
	v_cmp_le_u32_e32 vcc, s100, v3
	s_and_b64 s[0:1], vcc, s[8:9]
	s_bcnt1_i32_b64 s101, s[0:1]
	s_cmp_ge_u32 s101, 13
	s_cselect_b32 s98, s100, s98
	s_or_b32 s100, s98, 0x80000
	v_cmp_le_u32_e32 vcc, s100, v3
	s_and_b64 s[0:1], vcc, s[8:9]
	s_bcnt1_i32_b64 s101, s[0:1]
	s_cmp_ge_u32 s101, 13
	s_cselect_b32 s98, s100, s98
	s_or_b32 s100, s98, 0x40000
	v_cmp_le_u32_e32 vcc, s100, v3
	s_and_b64 s[0:1], vcc, s[8:9]
	s_bcnt1_i32_b64 s101, s[0:1]
	s_cmp_ge_u32 s101, 13
	s_cselect_b32 s98, s100, s98
	s_or_b32 s100, s98, 0x20000
	v_cmp_le_u32_e32 vcc, s100, v3
	s_and_b64 s[0:1], vcc, s[8:9]
	s_bcnt1_i32_b64 s101, s[0:1]
	s_cmp_ge_u32 s101, 13
	s_cselect_b32 s98, s100, s98
	s_or_b32 s100, s98, 0x10000
	v_cmp_le_u32_e32 vcc, s100, v3
	s_and_b64 s[0:1], vcc, s[8:9]
	s_bcnt1_i32_b64 s101, s[0:1]
	s_cmp_ge_u32 s101, 13
	s_cselect_b32 s98, s100, s98
	s_or_b32 s100, s98, 0x8000
	v_cmp_le_u32_e32 vcc, s100, v3
	s_and_b64 s[0:1], vcc, s[8:9]
	s_bcnt1_i32_b64 s101, s[0:1]
	s_cmp_ge_u32 s101, 13
	s_cselect_b32 s98, s100, s98
	s_or_b32 s100, s98, 0x4000
	v_cmp_le_u32_e32 vcc, s100, v3
	s_and_b64 s[0:1], vcc, s[8:9]
	s_bcnt1_i32_b64 s101, s[0:1]
	s_cmp_ge_u32 s101, 13
	s_cselect_b32 s98, s100, s98
	s_or_b32 s100, s98, 0x2000
	v_cmp_le_u32_e32 vcc, s100, v3
	s_and_b64 s[0:1], vcc, s[8:9]
	s_bcnt1_i32_b64 s101, s[0:1]
	s_cmp_ge_u32 s101, 13
	s_cselect_b32 s98, s100, s98
	s_or_b32 s100, s98, 0x1000
	v_cmp_le_u32_e32 vcc, s100, v3
	s_and_b64 s[0:1], vcc, s[8:9]
	s_bcnt1_i32_b64 s101, s[0:1]
	s_cmp_ge_u32 s101, 13
	s_cselect_b32 s98, s100, s98
	s_or_b32 s100, s98, 0x800
	v_cmp_le_u32_e32 vcc, s100, v3
	s_and_b64 s[0:1], vcc, s[8:9]
	s_bcnt1_i32_b64 s101, s[0:1]
	s_cmp_ge_u32 s101, 13
	s_cselect_b32 s98, s100, s98
	s_or_b32 s100, s98, 0x400
	v_cmp_le_u32_e32 vcc, s100, v3
	s_and_b64 s[0:1], vcc, s[8:9]
	s_bcnt1_i32_b64 s101, s[0:1]
	s_cmp_ge_u32 s101, 13
	s_cselect_b32 s98, s100, s98
	s_or_b32 s100, s98, 0x200
	v_cmp_le_u32_e32 vcc, s100, v3
	s_and_b64 s[0:1], vcc, s[8:9]
	s_bcnt1_i32_b64 s101, s[0:1]
	s_cmp_ge_u32 s101, 13
	s_cselect_b32 s98, s100, s98
	s_or_b32 s100, s98, 0x100
	v_cmp_le_u32_e32 vcc, s100, v3
	s_and_b64 s[0:1], vcc, s[8:9]
	s_bcnt1_i32_b64 s101, s[0:1]
	s_cmp_ge_u32 s101, 13
	s_cselect_b32 s98, s100, s98
	s_or_b32 s100, s98, 0x80
	v_cmp_le_u32_e32 vcc, s100, v3
	s_and_b64 s[0:1], vcc, s[8:9]
	s_bcnt1_i32_b64 s101, s[0:1]
	s_cmp_ge_u32 s101, 13
	s_cselect_b32 s98, s100, s98
	s_or_b32 s100, s98, 64
	v_cmp_le_u32_e32 vcc, s100, v3
	s_and_b64 s[0:1], vcc, s[8:9]
	s_bcnt1_i32_b64 s101, s[0:1]
	s_cmp_ge_u32 s101, 13
	s_cselect_b32 s98, s100, s98
	s_or_b32 s100, s98, 32
	v_cmp_le_u32_e32 vcc, s100, v3
	s_and_b64 s[0:1], vcc, s[8:9]
	s_bcnt1_i32_b64 s101, s[0:1]
	s_cmp_ge_u32 s101, 13
	s_cselect_b32 s98, s100, s98
	s_or_b32 s100, s98, 16
	v_cmp_le_u32_e32 vcc, s100, v3
	s_and_b64 s[0:1], vcc, s[8:9]
	s_bcnt1_i32_b64 s101, s[0:1]
	s_cmp_ge_u32 s101, 13
	s_cselect_b32 s98, s100, s98
	s_or_b32 s100, s98, 8
	v_cmp_le_u32_e32 vcc, s100, v3
	s_and_b64 s[0:1], vcc, s[8:9]
	s_bcnt1_i32_b64 s101, s[0:1]
	s_cmp_ge_u32 s101, 13
	s_cselect_b32 s98, s100, s98
	s_or_b32 s100, s98, 4
	v_cmp_le_u32_e32 vcc, s100, v3
	s_and_b64 s[0:1], vcc, s[8:9]
	s_bcnt1_i32_b64 s101, s[0:1]
	s_cmp_ge_u32 s101, 13
	s_cselect_b32 s98, s100, s98
	s_or_b32 s100, s98, 2
	v_cmp_le_u32_e32 vcc, s100, v3
	s_and_b64 s[0:1], vcc, s[8:9]
	s_bcnt1_i32_b64 s101, s[0:1]
	s_cmp_ge_u32 s101, 13
	s_cselect_b32 s98, s100, s98
	s_or_b32 s100, s98, 1
	v_cmp_le_u32_e32 vcc, s100, v3
	s_and_b64 s[0:1], vcc, s[8:9]
	s_bcnt1_i32_b64 s101, s[0:1]
	s_cmp_ge_u32 s101, 13
	s_cselect_b32 s98, s100, s98
	v_cmp_lt_u32_e32 vcc, s98, v3
	s_and_b64 s[0:1], vcc, s[8:9]
	s_bcnt1_i32_b64 s101, s[0:1]
	s_sub_i32 s99, 13, s101
	v_cmp_eq_u32_e32 vcc, s98, v3
	s_and_b64 vcc, vcc, s[8:9]
	s_nop 1
	v_mbcnt_lo_u32_b32 v4, vcc_lo, 0
	v_mbcnt_hi_u32_b32 v4, vcc_hi, v4
	v_cmp_gt_u32_e64 s[100:101], s99, v4
	s_and_b64 vcc, vcc, s[100:101]
	s_or_b64 vcc, vcc, s[0:1]
	s_or_b64 s[14:15], s[10:11], vcc
	s_or_b32 s14, s14, 1

; __device__ __forceinline__ float rdlane(float v, int l) { return __int_as_float(__builtin_amdgcn_readlane(__float_as_int(v), l)); }
; __device__ __forceinline__ void nsa_unit(Frame& F, int b, int g, int c) {
;     ...
;         for (int tt = 0; tt < 8; ++tt) {
;             const int tl = 8 * w + tt; unsigned long long mk;
;             if (c >= 16) {
;                 const bool cand = (lane >= 1) && (lane <= c - 2);
;                 const float v = cand ? impG[tl * 64 + lane] + impL[tl * 64 + lane] : -__builtin_inff();
;                 int rank = 0;
;                 for (int i = 0; i < 64; ++i) { const float vi = rdlane(v, i); rank += ((vi > v) || (vi == v && i < lane)) ? 1 : 0; }
;                 mk = __ballot(cand && rank < 13) | 1ull | (1ull << c) | (1ull << (c - 1));
;             } else mk = (2ull << c) - 1ull;
;             if (lane == 0) selm[tl] = mk;
;             wuni |= mk;
.LBB0_877:
	s_or_b64 exec, exec, s[0:1]
	v_ashrrev_i32_e32 v3, 31, v2
	v_or_b32_e32 v3, 0x80000000, v3
	v_xor_b32_e32 v3, v2, v3
	s_mov_b32 s98, 0
	s_or_b32 s100, s98, 0x80000000
	v_cmp_le_u32_e32 vcc, s100, v3
	s_and_b64 s[0:1], vcc, s[8:9]
	s_bcnt1_i32_b64 s101, s[0:1]
	s_cmp_ge_u32 s101, 13
	s_cselect_b32 s98, s100, s98
	s_or_b32 s100, s98, 0x40000000
	v_cmp_le_u32_e32 vcc, s100, v3
	s_and_b64 s[0:1], vcc, s[8:9]
	s_bcnt1_i32_b64 s101, s[0:1]
	s_cmp_ge_u32 s101, 13
	s_cselect_b32 s98, s100, s98
	s_or_b32 s100, s98, 0x20000000
	v_cmp_le_u32_e32 vcc, s100, v3
	s_and_b64 s[0:1], vcc, s[8:9]
	s_bcnt1_i32_b64 s101, s[0:1]
	s_cmp_ge_u32 s101, 13
	s_cselect_b32 s98, s100, s98
	s_or_b32 s100, s98, 0x10000000
	v_cmp_le_u32_e32 vcc, s100, v3
	s_and_b64 s[0:1], vcc, s[8:9]
	s_bcnt1_i32_b64 s101, s[0:1]
	s_cmp_ge_u32 s101, 13
	s_cselect_b32 s98, s100, s98
	s_or_b32 s100, s98, 0x8000000
	v_cmp_le_u32_e32 vcc, s100, v3
	s_and_b64 s[0:1], vcc, s[8:9]
	s_bcnt1_i32_b64 s101, s[0:1]
	s_cmp_ge_u32 s101, 13
	s_cselect_b32 s98, s100, s98
	s_or_b32 s100, s98, 0x4000000
	v_cmp_le_u32_e32 vcc, s100, v3
	s_and_b64 s[0:1], vcc, s[8:9]
	s_bcnt1_i32_b64 s101, s[0:1]
	s_cmp_ge_u32 s101, 13
	s_cselect_b32 s98, s100, s98
	s_or_b32 s100, s98, 0x2000000
	v_cmp_le_u32_e32 vcc, s100, v3
	s_and_b64 s[0:1], vcc, s[8:9]
	s_bcnt1_i32_b64 s101, s[0:1]
	s_cmp_ge_u32 s101, 13
	s_cselect_b32 s98, s100, s98
	s_or_b32 s100, s98, 0x1000000
	v_cmp_le_u32_e32 vcc, s100, v3
	s_and_b64 s[0:1], vcc, s[8:9]
	s_bcnt1_i32_b64 s101, s[0:1]
	s_cmp_ge_u32 s101, 13
	s_cselect_b32 s98, s100, s98
	s_or_b32 s100, s98, 0x800000
	v_cmp_le_u32_e32 vcc, s100, v3
	s_and_b64 s[0:1], vcc, s[8:9]
	s_bcnt1_i32_b64 s101, s[0:1]
	s_cmp_ge_u32 s101, 13
	s_cselect_b32 s98, s100, s98
	s_or_b32 s100, s98, 0x400000
	v_cmp_le_u32_e32 vcc, s100, v3
	s_and_b64 s[0:1], vcc, s[8:9]
	s_bcnt1_i32_b64 s101, s[0:1]
	s_cmp_ge_u32 s101, 13
	s_cselect_b32 s98, s100, s98
	s_or_b32 s100, s98, 0x200000
	v_cmp_le_u32_e32 vcc, s100, v3
	s_and_b64 s[0:1], vcc, s[8:9]
	s_bcnt1_i32_b64 s101, s[0:1]
	s_cmp_ge_u32 s101, 13
	s_cselect_b32 s98, s100, s98
	s_or_b32 s100, s98, 0x100000
	v_cmp_le_u32_e32 vcc, s100, v3
	s_and_b64 s[0:1], vcc, s[8:9]
	s_bcnt1_i32_b64 s101, s[0:1]
	s_cmp_ge_u32 s101, 13
	s_cselect_b32 s98, s100, s98
	s_or_b32 s100, s98, 0x80000
	v_cmp_le_u32_e32 vcc, s100, v3
	s_and_b64 s[0:1], vcc, s[8:9]
	s_bcnt1_i32_b64 s101, s[0:1]
	s_cmp_ge_u32 s101, 13
	s_cselect_b32 s98, s100, s98
	s_or_b32 s100, s98, 0x40000
	v_cmp_le_u32_e32 vcc, s100, v3
	s_and_b64 s[0:1], vcc, s[8:9]
	s_bcnt1_i32_b64 s101, s[0:1]
	s_cmp_ge_u32 s101, 13
	s_cselect_b32 s98, s100, s98
	s_or_b32 s100, s98, 0x20000
	v_cmp_le_u32_e32 vcc, s100, v3
	s_and_b64 s[0:1], vcc, s[8:9]
	s_bcnt1_i32_b64 s101, s[0:1]
	s_cmp_ge_u32 s101, 13
	s_cselect_b32 s98, s100, s98
	s_or_b32 s100, s98, 0x10000
	v_cmp_le_u32_e32 vcc, s100, v3
	s_and_b64 s[0:1], vcc, s[8:9]
	s_bcnt1_i32_b64 s101, s[0:1]
	s_cmp_ge_u32 s101, 13
	s_cselect_b32 s98, s100, s98
	s_or_b32 s100, s98, 0x8000
	v_cmp_le_u32_e32 vcc, s100, v3
	s_and_b64 s[0:1], vcc, s[8:9]
	s_bcnt1_i32_b64 s101, s[0:1]
	s_cmp_ge_u32 s101, 13
	s_cselect_b32 s98, s100, s98
	s_or_b32 s100, s98, 0x4000
	v_cmp_le_u32_e32 vcc, s100, v3
	s_and_b64 s[0:1], vcc, s[8:9]
	s_bcnt1_i32_b64 s101, s[0:1]
	s_cmp_ge_u32 s101, 13
	s_cselect_b32 s98, s100, s98
	s_or_b32 s100, s98, 0x2000
	v_cmp_le_u32_e32 vcc, s100, v3
	s_and_b64 s[0:1], vcc, s[8:9]
	s_bcnt1_i32_b64 s101, s[0:1]
	s_cmp_ge_u32 s101, 13
	s_cselect_b32 s98, s100, s98
	s_or_b32 s100, s98, 0x1000
	v_cmp_le_u32_e32 vcc, s100, v3
	s_and_b64 s[0:1], vcc, s[8:9]
	s_bcnt1_i32_b64 s101, s[0:1]
	s_cmp_ge_u32 s101, 13
	s_cselect_b32 s98, s100, s98
	s_or_b32 s100, s98, 0x800
	v_cmp_le_u32_e32 vcc, s100, v3
	s_and_b64 s[0:1], vcc, s[8:9]
	s_bcnt1_i32_b64 s101, s[0:1]
	s_cmp_ge_u32 s101, 13
	s_cselect_b32 s98, s100, s98
	s_or_b32 s100, s98, 0x400
	v_cmp_le_u32_e32 vcc, s100, v3
	s_and_b64 s[0:1], vcc, s[8:9]
	s_bcnt1_i32_b64 s101, s[0:1]
	s_cmp_ge_u32 s101, 13
	s_cselect_b32 s98, s100, s98
	s_or_b32 s100, s98, 0x200
	v_cmp_le_u32_e32 vcc, s100, v3
	s_and_b64 s[0:1], vcc, s[8:9]
	s_bcnt1_i32_b64 s101, s[0:1]
	s_cmp_ge_u32 s101, 13
	s_cselect_b32 s98, s100, s98
	s_or_b32 s100, s98, 0x100
	v_cmp_le_u32_e32 vcc, s100, v3
	s_and_b64 s[0:1], vcc, s[8:9]
	s_bcnt1_i32_b64 s101, s[0:1]
	s_cmp_ge_u32 s101, 13
	s_cselect_b32 s98, s100, s98
	s_or_b32 s100, s98, 0x80
	v_cmp_le_u32_e32 vcc, s100, v3
	s_and_b64 s[0:1], vcc, s[8:9]
	s_bcnt1_i32_b64 s101, s[0:1]
	s_cmp_ge_u32 s101, 13
	s_cselect_b32 s98, s100, s98
	s_or_b32 s100, s98, 64
	v_cmp_le_u32_e32 vcc, s100, v3
	s_and_b64 s[0:1], vcc, s[8:9]
	s_bcnt1_i32_b64 s101, s[0:1]
	s_cmp_ge_u32 s101, 13
	s_cselect_b32 s98, s100, s98
	s_or_b32 s100, s98, 32
	v_cmp_le_u32_e32 vcc, s100, v3
	s_and_b64 s[0:1], vcc, s[8:9]
	s_bcnt1_i32_b64 s101, s[0:1]
	s_cmp_ge_u32 s101, 13
	s_cselect_b32 s98, s100, s98
	s_or_b32 s100, s98, 16
	v_cmp_le_u32_e32 vcc, s100, v3
	s_and_b64 s[0:1], vcc, s[8:9]
	s_bcnt1_i32_b64 s101, s[0:1]
	s_cmp_ge_u32 s101, 13
	s_cselect_b32 s98, s100, s98
	s_or_b32 s100, s98, 8
	v_cmp_le_u32_e32 vcc, s100, v3
	s_and_b64 s[0:1], vcc, s[8:9]
	s_bcnt1_i32_b64 s101, s[0:1]
	s_cmp_ge_u32 s101, 13
	s_cselect_b32 s98, s100, s98
	s_or_b32 s100, s98, 4
	v_cmp_le_u32_e32 vcc, s100, v3
	s_and_b64 s[0:1], vcc, s[8:9]
	s_bcnt1_i32_b64 s101, s[0:1]
	s_cmp_ge_u32 s101, 13
	s_cselect_b32 s98, s100, s98
	s_or_b32 s100, s98, 2
	v_cmp_le_u32_e32 vcc, s100, v3
	s_and_b64 s[0:1], vcc, s[8:9]
	s_bcnt1_i32_b64 s101, s[0:1]
	s_cmp_ge_u32 s101, 13
	s_cselect_b32 s98, s100, s98
	s_or_b32 s100, s98, 1
	v_cmp_le_u32_e32 vcc, s100, v3
	s_and_b64 s[0:1], vcc, s[8:9]
	s_bcnt1_i32_b64 s101, s[0:1]
	s_cmp_ge_u32 s101, 13
	s_cselect_b32 s98, s100, s98
	v_cmp_lt_u32_e32 vcc, s98, v3
	s_and_b64 s[0:1], vcc, s[8:9]
	s_bcnt1_i32_b64 s101, s[0:1]
	s_sub_i32 s99, 13, s101
	v_cmp_eq_u32_e32 vcc, s98, v3
	s_and_b64 vcc, vcc, s[8:9]
	s_nop 1
	v_mbcnt_lo_u32_b32 v4, vcc_lo, 0
	v_mbcnt_hi_u32_b32 v4, vcc_hi, v4
	v_cmp_gt_u32_e64 s[100:101], s99, v4
	s_and_b64 vcc, vcc, s[100:101]
	s_or_b64 vcc, vcc, s[0:1]
	s_or_b64 s[16:17], s[10:11], vcc
	s_or_b32 s16, s16, 1

; __device__ __forceinline__ float rdlane(float v, int l) { return __int_as_float(__builtin_amdgcn_readlane(__float_as_int(v), l)); }
; __device__ __forceinline__ void nsa_unit(Frame& F, int b, int g, int c) {
;     ...
;         for (int tt = 0; tt < 8; ++tt) {
;             const int tl = 8 * w + tt; unsigned long long mk;
;             if (c >= 16) {
;                 const bool cand = (lane >= 1) && (lane <= c - 2);
;                 const float v = cand ? impG[tl * 64 + lane] + impL[tl * 64 + lane] : -__builtin_inff();
;                 int rank = 0;
;                 for (int i = 0; i < 64; ++i) { const float vi = rdlane(v, i); rank += ((vi > v) || (vi == v && i < lane)) ? 1 : 0; }
;                 mk = __ballot(cand && rank < 13) | 1ull | (1ull << c) | (1ull << (c - 1));
;             } else mk = (2ull << c) - 1ull;
;             if (lane == 0) selm[tl] = mk;
;             wuni |= mk;
.LBB0_885:
	s_or_b64 exec, exec, s[0:1]
	v_ashrrev_i32_e32 v3, 31, v2
	v_or_b32_e32 v3, 0x80000000, v3
	v_xor_b32_e32 v3, v2, v3
	s_mov_b32 s98, 0
	s_or_b32 s100, s98, 0x80000000
	v_cmp_le_u32_e32 vcc, s100, v3
	s_and_b64 s[0:1], vcc, s[8:9]
	s_bcnt1_i32_b64 s101, s[0:1]
	s_cmp_ge_u32 s101, 13
	s_cselect_b32 s98, s100, s98
	s_or_b32 s100, s98, 0x40000000
	v_cmp_le_u32_e32 vcc, s100, v3
	s_and_b64 s[0:1], vcc, s[8:9]
	s_bcnt1_i32_b64 s101, s[0:1]
	s_cmp_ge_u32 s101, 13
	s_cselect_b32 s98, s100, s98
	s_or_b32 s100, s98, 0x20000000
	v_cmp_le_u32_e32 vcc, s100, v3
	s_and_b64 s[0:1], vcc, s[8:9]
	s_bcnt1_i32_b64 s101, s[0:1]
	s_cmp_ge_u32 s101, 13
	s_cselect_b32 s98, s100, s98
	s_or_b32 s100, s98, 0x10000000
	v_cmp_le_u32_e32 vcc, s100, v3
	s_and_b64 s[0:1], vcc, s[8:9]
	s_bcnt1_i32_b64 s101, s[0:1]
	s_cmp_ge_u32 s101, 13
	s_cselect_b32 s98, s100, s98
	s_or_b32 s100, s98, 0x8000000
	v_cmp_le_u32_e32 vcc, s100, v3
	s_and_b64 s[0:1], vcc, s[8:9]
	s_bcnt1_i32_b64 s101, s[0:1]
	s_cmp_ge_u32 s101, 13
	s_cselect_b32 s98, s100, s98
	s_or_b32 s100, s98, 0x4000000
	v_cmp_le_u32_e32 vcc, s100, v3
	s_and_b64 s[0:1], vcc, s[8:9]
	s_bcnt1_i32_b64 s101, s[0:1]
	s_cmp_ge_u32 s101, 13
	s_cselect_b32 s98, s100, s98
	s_or_b32 s100, s98, 0x2000000
	v_cmp_le_u32_e32 vcc, s100, v3
	s_and_b64 s[0:1], vcc, s[8:9]
	s_bcnt1_i32_b64 s101, s[0:1]
	s_cmp_ge_u32 s101, 13
	s_cselect_b32 s98, s100, s98
	s_or_b32 s100, s98, 0x1000000
	v_cmp_le_u32_e32 vcc, s100, v3
	s_and_b64 s[0:1], vcc, s[8:9]
	s_bcnt1_i32_b64 s101, s[0:1]
	s_cmp_ge_u32 s101, 13
	s_cselect_b32 s98, s100, s98
	s_or_b32 s100, s98, 0x800000
	v_cmp_le_u32_e32 vcc, s100, v3
	s_and_b64 s[0:1], vcc, s[8:9]
	s_bcnt1_i32_b64 s101, s[0:1]
	s_cmp_ge_u32 s101, 13
	s_cselect_b32 s98, s100, s98
	s_or_b32 s100, s98, 0x400000
	v_cmp_le_u32_e32 vcc, s100, v3
	s_and_b64 s[0:1], vcc, s[8:9]
	s_bcnt1_i32_b64 s101, s[0:1]
	s_cmp_ge_u32 s101, 13
	s_cselect_b32 s98, s100, s98
	s_or_b32 s100, s98, 0x200000
	v_cmp_le_u32_e32 vcc, s100, v3
	s_and_b64 s[0:1], vcc, s[8:9]
	s_bcnt1_i32_b64 s101, s[0:1]
	s_cmp_ge_u32 s101, 13
	s_cselect_b32 s98, s100, s98
	s_or_b32 s100, s98, 0x100000
	v_cmp_le_u32_e32 vcc, s100, v3
	s_and_b64 s[0:1], vcc, s[8:9]
	s_bcnt1_i32_b64 s101, s[0:1]
	s_cmp_ge_u32 s101, 13
	s_cselect_b32 s98, s100, s98
	s_or_b32 s100, s98, 0x80000
	v_cmp_le_u32_e32 vcc, s100, v3
	s_and_b64 s[0:1], vcc, s[8:9]
	s_bcnt1_i32_b64 s101, s[0:1]
	s_cmp_ge_u32 s101, 13
	s_cselect_b32 s98, s100, s98
	s_or_b32 s100, s98, 0x40000
	v_cmp_le_u32_e32 vcc, s100, v3
	s_and_b64 s[0:1], vcc, s[8:9]
	s_bcnt1_i32_b64 s101, s[0:1]
	s_cmp_ge_u32 s101, 13
	s_cselect_b32 s98, s100, s98
	s_or_b32 s100, s98, 0x20000
	v_cmp_le_u32_e32 vcc, s100, v3
	s_and_b64 s[0:1], vcc, s[8:9]
	s_bcnt1_i32_b64 s101, s[0:1]
	s_cmp_ge_u32 s101, 13
	s_cselect_b32 s98, s100, s98
	s_or_b32 s100, s98, 0x10000
	v_cmp_le_u32_e32 vcc, s100, v3
	s_and_b64 s[0:1], vcc, s[8:9]
	s_bcnt1_i32_b64 s101, s[0:1]
	s_cmp_ge_u32 s101, 13
	s_cselect_b32 s98, s100, s98
	s_or_b32 s100, s98, 0x8000
	v_cmp_le_u32_e32 vcc, s100, v3
	s_and_b64 s[0:1], vcc, s[8:9]
	s_bcnt1_i32_b64 s101, s[0:1]
	s_cmp_ge_u32 s101, 13
	s_cselect_b32 s98, s100, s98
	s_or_b32 s100, s98, 0x4000
	v_cmp_le_u32_e32 vcc, s100, v3
	s_and_b64 s[0:1], vcc, s[8:9]
	s_bcnt1_i32_b64 s101, s[0:1]
	s_cmp_ge_u32 s101, 13
	s_cselect_b32 s98, s100, s98
	s_or_b32 s100, s98, 0x2000
	v_cmp_le_u32_e32 vcc, s100, v3
	s_and_b64 s[0:1], vcc, s[8:9]
	s_bcnt1_i32_b64 s101, s[0:1]
	s_cmp_ge_u32 s101, 13
	s_cselect_b32 s98, s100, s98
	s_or_b32 s100, s98, 0x1000
	v_cmp_le_u32_e32 vcc, s100, v3
	s_and_b64 s[0:1], vcc, s[8:9]
	s_bcnt1_i32_b64 s101, s[0:1]
	s_cmp_ge_u32 s101, 13
	s_cselect_b32 s98, s100, s98
	s_or_b32 s100, s98, 0x800
	v_cmp_le_u32_e32 vcc, s100, v3
	s_and_b64 s[0:1], vcc, s[8:9]
	s_bcnt1_i32_b64 s101, s[0:1]
	s_cmp_ge_u32 s101, 13
	s_cselect_b32 s98, s100, s98
	s_or_b32 s100, s98, 0x400
	v_cmp_le_u32_e32 vcc, s100, v3
	s_and_b64 s[0:1], vcc, s[8:9]
	s_bcnt1_i32_b64 s101, s[0:1]
	s_cmp_ge_u32 s101, 13
	s_cselect_b32 s98, s100, s98
	s_or_b32 s100, s98, 0x200
	v_cmp_le_u32_e32 vcc, s100, v3
	s_and_b64 s[0:1], vcc, s[8:9]
	s_bcnt1_i32_b64 s101, s[0:1]
	s_cmp_ge_u32 s101, 13
	s_cselect_b32 s98, s100, s98
	s_or_b32 s100, s98, 0x100
	v_cmp_le_u32_e32 vcc, s100, v3
	s_and_b64 s[0:1], vcc, s[8:9]
	s_bcnt1_i32_b64 s101, s[0:1]
	s_cmp_ge_u32 s101, 13
	s_cselect_b32 s98, s100, s98
	s_or_b32 s100, s98, 0x80
	v_cmp_le_u32_e32 vcc, s100, v3
	s_and_b64 s[0:1], vcc, s[8:9]
	s_bcnt1_i32_b64 s101, s[0:1]
	s_cmp_ge_u32 s101, 13
	s_cselect_b32 s98, s100, s98
	s_or_b32 s100, s98, 64
	v_cmp_le_u32_e32 vcc, s100, v3
	s_and_b64 s[0:1], vcc, s[8:9]
	s_bcnt1_i32_b64 s101, s[0:1]
	s_cmp_ge_u32 s101, 13
	s_cselect_b32 s98, s100, s98
	s_or_b32 s100, s98, 32
	v_cmp_le_u32_e32 vcc, s100, v3
	s_and_b64 s[0:1], vcc, s[8:9]
	s_bcnt1_i32_b64 s101, s[0:1]
	s_cmp_ge_u32 s101, 13
	s_cselect_b32 s98, s100, s98
	s_or_b32 s100, s98, 16
	v_cmp_le_u32_e32 vcc, s100, v3
	s_and_b64 s[0:1], vcc, s[8:9]
	s_bcnt1_i32_b64 s101, s[0:1]
	s_cmp_ge_u32 s101, 13
	s_cselect_b32 s98, s100, s98
	s_or_b32 s100, s98, 8
	v_cmp_le_u32_e32 vcc, s100, v3
	s_and_b64 s[0:1], vcc, s[8:9]
	s_bcnt1_i32_b64 s101, s[0:1]
	s_cmp_ge_u32 s101, 13
	s_cselect_b32 s98, s100, s98
	s_or_b32 s100, s98, 4
	v_cmp_le_u32_e32 vcc, s100, v3
	s_and_b64 s[0:1], vcc, s[8:9]
	s_bcnt1_i32_b64 s101, s[0:1]
	s_cmp_ge_u32 s101, 13
	s_cselect_b32 s98, s100, s98
	s_or_b32 s100, s98, 2
	v_cmp_le_u32_e32 vcc, s100, v3
	s_and_b64 s[0:1], vcc, s[8:9]
	s_bcnt1_i32_b64 s101, s[0:1]
	s_cmp_ge_u32 s101, 13
	s_cselect_b32 s98, s100, s98
	s_or_b32 s100, s98, 1
	v_cmp_le_u32_e32 vcc, s100, v3
	s_and_b64 s[0:1], vcc, s[8:9]
	s_bcnt1_i32_b64 s101, s[0:1]
	s_cmp_ge_u32 s101, 13
	s_cselect_b32 s98, s100, s98
	v_cmp_lt_u32_e32 vcc, s98, v3
	s_and_b64 s[0:1], vcc, s[8:9]
	s_bcnt1_i32_b64 s101, s[0:1]
	s_sub_i32 s99, 13, s101
	v_cmp_eq_u32_e32 vcc, s98, v3
	s_and_b64 vcc, vcc, s[8:9]
	s_nop 1
	v_mbcnt_lo_u32_b32 v4, vcc_lo, 0
	v_mbcnt_hi_u32_b32 v4, vcc_hi, v4
	v_cmp_gt_u32_e64 s[100:101], s99, v4
	s_and_b64 vcc, vcc, s[100:101]
	s_or_b64 vcc, vcc, s[0:1]
	s_or_b64 s[18:19], s[10:11], vcc
	s_or_b32 s18, s18, 1

; __device__ __forceinline__ float rdlane(float v, int l) { return __int_as_float(__builtin_amdgcn_readlane(__float_as_int(v), l)); }
; __device__ __forceinline__ void nsa_unit(Frame& F, int b, int g, int c) {
;     ...
;         for (int tt = 0; tt < 8; ++tt) {
;             const int tl = 8 * w + tt; unsigned long long mk;
;             if (c >= 16) {
;                 const bool cand = (lane >= 1) && (lane <= c - 2);
;                 const float v = cand ? impG[tl * 64 + lane] + impL[tl * 64 + lane] : -__builtin_inff();
;                 int rank = 0;
;                 for (int i = 0; i < 64; ++i) { const float vi = rdlane(v, i); rank += ((vi > v) || (vi == v && i < lane)) ? 1 : 0; }
;                 mk = __ballot(cand && rank < 13) | 1ull | (1ull << c) | (1ull << (c - 1));
;             } else mk = (2ull << c) - 1ull;
;             if (lane == 0) selm[tl] = mk;
;             wuni |= mk;
.LBB0_893:
	s_or_b64 exec, exec, s[0:1]
	v_ashrrev_i32_e32 v3, 31, v2
	v_or_b32_e32 v3, 0x80000000, v3
	v_xor_b32_e32 v3, v2, v3
	s_mov_b32 s98, 0
	s_or_b32 s100, s98, 0x80000000
	v_cmp_le_u32_e32 vcc, s100, v3
	s_and_b64 s[0:1], vcc, s[8:9]
	s_bcnt1_i32_b64 s101, s[0:1]
	s_cmp_ge_u32 s101, 13
	s_cselect_b32 s98, s100, s98
	s_or_b32 s100, s98, 0x40000000
	v_cmp_le_u32_e32 vcc, s100, v3
	s_and_b64 s[0:1], vcc, s[8:9]
	s_bcnt1_i32_b64 s101, s[0:1]
	s_cmp_ge_u32 s101, 13
	s_cselect_b32 s98, s100, s98
	s_or_b32 s100, s98, 0x20000000
	v_cmp_le_u32_e32 vcc, s100, v3
	s_and_b64 s[0:1], vcc, s[8:9]
	s_bcnt1_i32_b64 s101, s[0:1]
	s_cmp_ge_u32 s101, 13
	s_cselect_b32 s98, s100, s98
	s_or_b32 s100, s98, 0x10000000
	v_cmp_le_u32_e32 vcc, s100, v3
	s_and_b64 s[0:1], vcc, s[8:9]
	s_bcnt1_i32_b64 s101, s[0:1]
	s_cmp_ge_u32 s101, 13
	s_cselect_b32 s98, s100, s98
	s_or_b32 s100, s98, 0x8000000
	v_cmp_le_u32_e32 vcc, s100, v3
	s_and_b64 s[0:1], vcc, s[8:9]
	s_bcnt1_i32_b64 s101, s[0:1]
	s_cmp_ge_u32 s101, 13
	s_cselect_b32 s98, s100, s98
	s_or_b32 s100, s98, 0x4000000
	v_cmp_le_u32_e32 vcc, s100, v3
	s_and_b64 s[0:1], vcc, s[8:9]
	s_bcnt1_i32_b64 s101, s[0:1]
	s_cmp_ge_u32 s101, 13
	s_cselect_b32 s98, s100, s98
	s_or_b32 s100, s98, 0x2000000
	v_cmp_le_u32_e32 vcc, s100, v3
	s_and_b64 s[0:1], vcc, s[8:9]
	s_bcnt1_i32_b64 s101, s[0:1]
	s_cmp_ge_u32 s101, 13
	s_cselect_b32 s98, s100, s98
	s_or_b32 s100, s98, 0x1000000
	v_cmp_le_u32_e32 vcc, s100, v3
	s_and_b64 s[0:1], vcc, s[8:9]
	s_bcnt1_i32_b64 s101, s[0:1]
	s_cmp_ge_u32 s101, 13
	s_cselect_b32 s98, s100, s98
	s_or_b32 s100, s98, 0x800000
	v_cmp_le_u32_e32 vcc, s100, v3
	s_and_b64 s[0:1], vcc, s[8:9]
	s_bcnt1_i32_b64 s101, s[0:1]
	s_cmp_ge_u32 s101, 13
	s_cselect_b32 s98, s100, s98
	s_or_b32 s100, s98, 0x400000
	v_cmp_le_u32_e32 vcc, s100, v3
	s_and_b64 s[0:1], vcc, s[8:9]
	s_bcnt1_i32_b64 s101, s[0:1]
	s_cmp_ge_u32 s101, 13
	s_cselect_b32 s98, s100, s98
	s_or_b32 s100, s98, 0x200000
	v_cmp_le_u32_e32 vcc, s100, v3
	s_and_b64 s[0:1], vcc, s[8:9]
	s_bcnt1_i32_b64 s101, s[0:1]
	s_cmp_ge_u32 s101, 13
	s_cselect_b32 s98, s100, s98
	s_or_b32 s100, s98, 0x100000
	v_cmp_le_u32_e32 vcc, s100, v3
	s_and_b64 s[0:1], vcc, s[8:9]
	s_bcnt1_i32_b64 s101, s[0:1]
	s_cmp_ge_u32 s101, 13
	s_cselect_b32 s98, s100, s98
	s_or_b32 s100, s98, 0x80000
	v_cmp_le_u32_e32 vcc, s100, v3
	s_and_b64 s[0:1], vcc, s[8:9]
	s_bcnt1_i32_b64 s101, s[0:1]
	s_cmp_ge_u32 s101, 13
	s_cselect_b32 s98, s100, s98
	s_or_b32 s100, s98, 0x40000
	v_cmp_le_u32_e32 vcc, s100, v3
	s_and_b64 s[0:1], vcc, s[8:9]
	s_bcnt1_i32_b64 s101, s[0:1]
	s_cmp_ge_u32 s101, 13
	s_cselect_b32 s98, s100, s98
	s_or_b32 s100, s98, 0x20000
	v_cmp_le_u32_e32 vcc, s100, v3
	s_and_b64 s[0:1], vcc, s[8:9]
	s_bcnt1_i32_b64 s101, s[0:1]
	s_cmp_ge_u32 s101, 13
	s_cselect_b32 s98, s100, s98
	s_or_b32 s100, s98, 0x10000
	v_cmp_le_u32_e32 vcc, s100, v3
	s_and_b64 s[0:1], vcc, s[8:9]
	s_bcnt1_i32_b64 s101, s[0:1]
	s_cmp_ge_u32 s101, 13
	s_cselect_b32 s98, s100, s98
	s_or_b32 s100, s98, 0x8000
	v_cmp_le_u32_e32 vcc, s100, v3
	s_and_b64 s[0:1], vcc, s[8:9]
	s_bcnt1_i32_b64 s101, s[0:1]
	s_cmp_ge_u32 s101, 13
	s_cselect_b32 s98, s100, s98
	s_or_b32 s100, s98, 0x4000
	v_cmp_le_u32_e32 vcc, s100, v3
	s_and_b64 s[0:1], vcc, s[8:9]
	s_bcnt1_i32_b64 s101, s[0:1]
	s_cmp_ge_u32 s101, 13
	s_cselect_b32 s98, s100, s98
	s_or_b32 s100, s98, 0x2000
	v_cmp_le_u32_e32 vcc, s100, v3
	s_and_b64 s[0:1], vcc, s[8:9]
	s_bcnt1_i32_b64 s101, s[0:1]
	s_cmp_ge_u32 s101, 13
	s_cselect_b32 s98, s100, s98
	s_or_b32 s100, s98, 0x1000
	v_cmp_le_u32_e32 vcc, s100, v3
	s_and_b64 s[0:1], vcc, s[8:9]
	s_bcnt1_i32_b64 s101, s[0:1]
	s_cmp_ge_u32 s101, 13
	s_cselect_b32 s98, s100, s98
	s_or_b32 s100, s98, 0x800
	v_cmp_le_u32_e32 vcc, s100, v3
	s_and_b64 s[0:1], vcc, s[8:9]
	s_bcnt1_i32_b64 s101, s[0:1]
	s_cmp_ge_u32 s101, 13
	s_cselect_b32 s98, s100, s98
	s_or_b32 s100, s98, 0x400
	v_cmp_le_u32_e32 vcc, s100, v3
	s_and_b64 s[0:1], vcc, s[8:9]
	s_bcnt1_i32_b64 s101, s[0:1]
	s_cmp_ge_u32 s101, 13
	s_cselect_b32 s98, s100, s98
	s_or_b32 s100, s98, 0x200
	v_cmp_le_u32_e32 vcc, s100, v3
	s_and_b64 s[0:1], vcc, s[8:9]
	s_bcnt1_i32_b64 s101, s[0:1]
	s_cmp_ge_u32 s101, 13
	s_cselect_b32 s98, s100, s98
	s_or_b32 s100, s98, 0x100
	v_cmp_le_u32_e32 vcc, s100, v3
	s_and_b64 s[0:1], vcc, s[8:9]
	s_bcnt1_i32_b64 s101, s[0:1]
	s_cmp_ge_u32 s101, 13
	s_cselect_b32 s98, s100, s98
	s_or_b32 s100, s98, 0x80
	v_cmp_le_u32_e32 vcc, s100, v3
	s_and_b64 s[0:1], vcc, s[8:9]
	s_bcnt1_i32_b64 s101, s[0:1]
	s_cmp_ge_u32 s101, 13
	s_cselect_b32 s98, s100, s98
	s_or_b32 s100, s98, 64
	v_cmp_le_u32_e32 vcc, s100, v3
	s_and_b64 s[0:1], vcc, s[8:9]
	s_bcnt1_i32_b64 s101, s[0:1]
	s_cmp_ge_u32 s101, 13
	s_cselect_b32 s98, s100, s98
	s_or_b32 s100, s98, 32
	v_cmp_le_u32_e32 vcc, s100, v3
	s_and_b64 s[0:1], vcc, s[8:9]
	s_bcnt1_i32_b64 s101, s[0:1]
	s_cmp_ge_u32 s101, 13
	s_cselect_b32 s98, s100, s98
	s_or_b32 s100, s98, 16
	v_cmp_le_u32_e32 vcc, s100, v3
	s_and_b64 s[0:1], vcc, s[8:9]
	s_bcnt1_i32_b64 s101, s[0:1]
	s_cmp_ge_u32 s101, 13
	s_cselect_b32 s98, s100, s98
	s_or_b32 s100, s98, 8
	v_cmp_le_u32_e32 vcc, s100, v3
	s_and_b64 s[0:1], vcc, s[8:9]
	s_bcnt1_i32_b64 s101, s[0:1]
	s_cmp_ge_u32 s101, 13
	s_cselect_b32 s98, s100, s98
	s_or_b32 s100, s98, 4
	v_cmp_le_u32_e32 vcc, s100, v3
	s_and_b64 s[0:1], vcc, s[8:9]
	s_bcnt1_i32_b64 s101, s[0:1]
	s_cmp_ge_u32 s101, 13
	s_cselect_b32 s98, s100, s98
	s_or_b32 s100, s98, 2
	v_cmp_le_u32_e32 vcc, s100, v3
	s_and_b64 s[0:1], vcc, s[8:9]
	s_bcnt1_i32_b64 s101, s[0:1]
	s_cmp_ge_u32 s101, 13
	s_cselect_b32 s98, s100, s98
	s_or_b32 s100, s98, 1
	v_cmp_le_u32_e32 vcc, s100, v3
	s_and_b64 s[0:1], vcc, s[8:9]
	s_bcnt1_i32_b64 s101, s[0:1]
	s_cmp_ge_u32 s101, 13
	s_cselect_b32 s98, s100, s98
	v_cmp_lt_u32_e32 vcc, s98, v3
	s_and_b64 s[0:1], vcc, s[8:9]
	s_bcnt1_i32_b64 s101, s[0:1]
	s_sub_i32 s99, 13, s101
	v_cmp_eq_u32_e32 vcc, s98, v3
	s_and_b64 vcc, vcc, s[8:9]
	s_nop 1
	v_mbcnt_lo_u32_b32 v4, vcc_lo, 0
	v_mbcnt_hi_u32_b32 v4, vcc_hi, v4
	v_cmp_gt_u32_e64 s[100:101], s99, v4
	s_and_b64 vcc, vcc, s[100:101]
	s_or_b64 vcc, vcc, s[0:1]
	s_or_b64 s[20:21], s[10:11], vcc
	s_or_b32 s20, s20, 1

; __device__ __forceinline__ float rdlane(float v, int l) { return __int_as_float(__builtin_amdgcn_readlane(__float_as_int(v), l)); }
; __device__ __forceinline__ void nsa_unit(Frame& F, int b, int g, int c) {
;     ...
;         for (int tt = 0; tt < 8; ++tt) {
;             const int tl = 8 * w + tt; unsigned long long mk;
;             if (c >= 16) {
;                 const bool cand = (lane >= 1) && (lane <= c - 2);
;                 const float v = cand ? impG[tl * 64 + lane] + impL[tl * 64 + lane] : -__builtin_inff();
;                 int rank = 0;
;                 for (int i = 0; i < 64; ++i) { const float vi = rdlane(v, i); rank += ((vi > v) || (vi == v && i < lane)) ? 1 : 0; }
;                 mk = __ballot(cand && rank < 13) | 1ull | (1ull << c) | (1ull << (c - 1));
;             } else mk = (2ull << c) - 1ull;
;             if (lane == 0) selm[tl] = mk;
;             wuni |= mk;
.LBB0_901:
	s_or_b64 exec, exec, s[0:1]
	v_ashrrev_i32_e32 v3, 31, v2
	v_or_b32_e32 v3, 0x80000000, v3
	v_xor_b32_e32 v3, v2, v3
	s_mov_b32 s98, 0
	s_or_b32 s100, s98, 0x80000000
	v_cmp_le_u32_e32 vcc, s100, v3
	s_and_b64 s[0:1], vcc, s[8:9]
	s_bcnt1_i32_b64 s101, s[0:1]
	s_cmp_ge_u32 s101, 13
	s_cselect_b32 s98, s100, s98
	s_or_b32 s100, s98, 0x40000000
	v_cmp_le_u32_e32 vcc, s100, v3
	s_and_b64 s[0:1], vcc, s[8:9]
	s_bcnt1_i32_b64 s101, s[0:1]
	s_cmp_ge_u32 s101, 13
	s_cselect_b32 s98, s100, s98
	s_or_b32 s100, s98, 0x20000000
	v_cmp_le_u32_e32 vcc, s100, v3
	s_and_b64 s[0:1], vcc, s[8:9]
	s_bcnt1_i32_b64 s101, s[0:1]
	s_cmp_ge_u32 s101, 13
	s_cselect_b32 s98, s100, s98
	s_or_b32 s100, s98, 0x10000000
	v_cmp_le_u32_e32 vcc, s100, v3
	s_and_b64 s[0:1], vcc, s[8:9]
	s_bcnt1_i32_b64 s101, s[0:1]
	s_cmp_ge_u32 s101, 13
	s_cselect_b32 s98, s100, s98
	s_or_b32 s100, s98, 0x8000000
	v_cmp_le_u32_e32 vcc, s100, v3
	s_and_b64 s[0:1], vcc, s[8:9]
	s_bcnt1_i32_b64 s101, s[0:1]
	s_cmp_ge_u32 s101, 13
	s_cselect_b32 s98, s100, s98
	s_or_b32 s100, s98, 0x4000000
	v_cmp_le_u32_e32 vcc, s100, v3
	s_and_b64 s[0:1], vcc, s[8:9]
	s_bcnt1_i32_b64 s101, s[0:1]
	s_cmp_ge_u32 s101, 13
	s_cselect_b32 s98, s100, s98
	s_or_b32 s100, s98, 0x2000000
	v_cmp_le_u32_e32 vcc, s100, v3
	s_and_b64 s[0:1], vcc, s[8:9]
	s_bcnt1_i32_b64 s101, s[0:1]
	s_cmp_ge_u32 s101, 13
	s_cselect_b32 s98, s100, s98
	s_or_b32 s100, s98, 0x1000000
	v_cmp_le_u32_e32 vcc, s100, v3
	s_and_b64 s[0:1], vcc, s[8:9]
	s_bcnt1_i32_b64 s101, s[0:1]
	s_cmp_ge_u32 s101, 13
	s_cselect_b32 s98, s100, s98
	s_or_b32 s100, s98, 0x800000
	v_cmp_le_u32_e32 vcc, s100, v3
	s_and_b64 s[0:1], vcc, s[8:9]
	s_bcnt1_i32_b64 s101, s[0:1]
	s_cmp_ge_u32 s101, 13
	s_cselect_b32 s98, s100, s98
	s_or_b32 s100, s98, 0x400000
	v_cmp_le_u32_e32 vcc, s100, v3
	s_and_b64 s[0:1], vcc, s[8:9]
	s_bcnt1_i32_b64 s101, s[0:1]
	s_cmp_ge_u32 s101, 13
	s_cselect_b32 s98, s100, s98
	s_or_b32 s100, s98, 0x200000
	v_cmp_le_u32_e32 vcc, s100, v3
	s_and_b64 s[0:1], vcc, s[8:9]
	s_bcnt1_i32_b64 s101, s[0:1]
	s_cmp_ge_u32 s101, 13
	s_cselect_b32 s98, s100, s98
	s_or_b32 s100, s98, 0x100000
	v_cmp_le_u32_e32 vcc, s100, v3
	s_and_b64 s[0:1], vcc, s[8:9]
	s_bcnt1_i32_b64 s101, s[0:1]
	s_cmp_ge_u32 s101, 13
	s_cselect_b32 s98, s100, s98
	s_or_b32 s100, s98, 0x80000
	v_cmp_le_u32_e32 vcc, s100, v3
	s_and_b64 s[0:1], vcc, s[8:9]
	s_bcnt1_i32_b64 s101, s[0:1]
	s_cmp_ge_u32 s101, 13
	s_cselect_b32 s98, s100, s98
	s_or_b32 s100, s98, 0x40000
	v_cmp_le_u32_e32 vcc, s100, v3
	s_and_b64 s[0:1], vcc, s[8:9]
	s_bcnt1_i32_b64 s101, s[0:1]
	s_cmp_ge_u32 s101, 13
	s_cselect_b32 s98, s100, s98
	s_or_b32 s100, s98, 0x20000
	v_cmp_le_u32_e32 vcc, s100, v3
	s_and_b64 s[0:1], vcc, s[8:9]
	s_bcnt1_i32_b64 s101, s[0:1]
	s_cmp_ge_u32 s101, 13
	s_cselect_b32 s98, s100, s98
	s_or_b32 s100, s98, 0x10000
	v_cmp_le_u32_e32 vcc, s100, v3
	s_and_b64 s[0:1], vcc, s[8:9]
	s_bcnt1_i32_b64 s101, s[0:1]
	s_cmp_ge_u32 s101, 13
	s_cselect_b32 s98, s100, s98
	s_or_b32 s100, s98, 0x8000
	v_cmp_le_u32_e32 vcc, s100, v3
	s_and_b64 s[0:1], vcc, s[8:9]
	s_bcnt1_i32_b64 s101, s[0:1]
	s_cmp_ge_u32 s101, 13
	s_cselect_b32 s98, s100, s98
	s_or_b32 s100, s98, 0x4000
	v_cmp_le_u32_e32 vcc, s100, v3
	s_and_b64 s[0:1], vcc, s[8:9]
	s_bcnt1_i32_b64 s101, s[0:1]
	s_cmp_ge_u32 s101, 13
	s_cselect_b32 s98, s100, s98
	s_or_b32 s100, s98, 0x2000
	v_cmp_le_u32_e32 vcc, s100, v3
	s_and_b64 s[0:1], vcc, s[8:9]
	s_bcnt1_i32_b64 s101, s[0:1]
	s_cmp_ge_u32 s101, 13
	s_cselect_b32 s98, s100, s98
	s_or_b32 s100, s98, 0x1000
	v_cmp_le_u32_e32 vcc, s100, v3
	s_and_b64 s[0:1], vcc, s[8:9]
	s_bcnt1_i32_b64 s101, s[0:1]
	s_cmp_ge_u32 s101, 13
	s_cselect_b32 s98, s100, s98
	s_or_b32 s100, s98, 0x800
	v_cmp_le_u32_e32 vcc, s100, v3
	s_and_b64 s[0:1], vcc, s[8:9]
	s_bcnt1_i32_b64 s101, s[0:1]
	s_cmp_ge_u32 s101, 13
	s_cselect_b32 s98, s100, s98
	s_or_b32 s100, s98, 0x400
	v_cmp_le_u32_e32 vcc, s100, v3
	s_and_b64 s[0:1], vcc, s[8:9]
	s_bcnt1_i32_b64 s101, s[0:1]
	s_cmp_ge_u32 s101, 13
	s_cselect_b32 s98, s100, s98
	s_or_b32 s100, s98, 0x200
	v_cmp_le_u32_e32 vcc, s100, v3
	s_and_b64 s[0:1], vcc, s[8:9]
	s_bcnt1_i32_b64 s101, s[0:1]
	s_cmp_ge_u32 s101, 13
	s_cselect_b32 s98, s100, s98
	s_or_b32 s100, s98, 0x100
	v_cmp_le_u32_e32 vcc, s100, v3
	s_and_b64 s[0:1], vcc, s[8:9]
	s_bcnt1_i32_b64 s101, s[0:1]
	s_cmp_ge_u32 s101, 13
	s_cselect_b32 s98, s100, s98
	s_or_b32 s100, s98, 0x80
	v_cmp_le_u32_e32 vcc, s100, v3
	s_and_b64 s[0:1], vcc, s[8:9]
	s_bcnt1_i32_b64 s101, s[0:1]
	s_cmp_ge_u32 s101, 13
	s_cselect_b32 s98, s100, s98
	s_or_b32 s100, s98, 64
	v_cmp_le_u32_e32 vcc, s100, v3
	s_and_b64 s[0:1], vcc, s[8:9]
	s_bcnt1_i32_b64 s101, s[0:1]
	s_cmp_ge_u32 s101, 13
	s_cselect_b32 s98, s100, s98
	s_or_b32 s100, s98, 32
	v_cmp_le_u32_e32 vcc, s100, v3
	s_and_b64 s[0:1], vcc, s[8:9]
	s_bcnt1_i32_b64 s101, s[0:1]
	s_cmp_ge_u32 s101, 13
	s_cselect_b32 s98, s100, s98
	s_or_b32 s100, s98, 16
	v_cmp_le_u32_e32 vcc, s100, v3
	s_and_b64 s[0:1], vcc, s[8:9]
	s_bcnt1_i32_b64 s101, s[0:1]
	s_cmp_ge_u32 s101, 13
	s_cselect_b32 s98, s100, s98
	s_or_b32 s100, s98, 8
	v_cmp_le_u32_e32 vcc, s100, v3
	s_and_b64 s[0:1], vcc, s[8:9]
	s_bcnt1_i32_b64 s101, s[0:1]
	s_cmp_ge_u32 s101, 13
	s_cselect_b32 s98, s100, s98
	s_or_b32 s100, s98, 4
	v_cmp_le_u32_e32 vcc, s100, v3
	s_and_b64 s[0:1], vcc, s[8:9]
	s_bcnt1_i32_b64 s101, s[0:1]
	s_cmp_ge_u32 s101, 13
	s_cselect_b32 s98, s100, s98
	s_or_b32 s100, s98, 2
	v_cmp_le_u32_e32 vcc, s100, v3
	s_and_b64 s[0:1], vcc, s[8:9]
	s_bcnt1_i32_b64 s101, s[0:1]
	s_cmp_ge_u32 s101, 13
	s_cselect_b32 s98, s100, s98
	s_or_b32 s100, s98, 1
	v_cmp_le_u32_e32 vcc, s100, v3
	s_and_b64 s[0:1], vcc, s[8:9]
	s_bcnt1_i32_b64 s101, s[0:1]
	s_cmp_ge_u32 s101, 13
	s_cselect_b32 s98, s100, s98
	v_cmp_lt_u32_e32 vcc, s98, v3
	s_and_b64 s[0:1], vcc, s[8:9]
	s_bcnt1_i32_b64 s101, s[0:1]
	s_sub_i32 s99, 13, s101
	v_cmp_eq_u32_e32 vcc, s98, v3
	s_and_b64 vcc, vcc, s[8:9]
	s_nop 1
	v_mbcnt_lo_u32_b32 v4, vcc_lo, 0
	v_mbcnt_hi_u32_b32 v4, vcc_hi, v4
	v_cmp_gt_u32_e64 s[100:101], s99, v4
	s_and_b64 vcc, vcc, s[100:101]
	s_or_b64 vcc, vcc, s[0:1]
	s_or_b64 s[22:23], s[10:11], vcc
	s_or_b32 s22, s22, 1

; __device__ __forceinline__ float rdlane(float v, int l) { return __int_as_float(__builtin_amdgcn_readlane(__float_as_int(v), l)); }
; __device__ __forceinline__ void nsa_unit(Frame& F, int b, int g, int c) {
;     ...
;         for (int tt = 0; tt < 8; ++tt) {
;             const int tl = 8 * w + tt; unsigned long long mk;
;             if (c >= 16) {
;                 const bool cand = (lane >= 1) && (lane <= c - 2);
;                 const float v = cand ? impG[tl * 64 + lane] + impL[tl * 64 + lane] : -__builtin_inff();
;                 int rank = 0;
;                 for (int i = 0; i < 64; ++i) { const float vi = rdlane(v, i); rank += ((vi > v) || (vi == v && i < lane)) ? 1 : 0; }
;                 mk = __ballot(cand && rank < 13) | 1ull | (1ull << c) | (1ull << (c - 1));
;             } else mk = (2ull << c) - 1ull;
;             if (lane == 0) selm[tl] = mk;
;             wuni |= mk;
.LBB0_909:
	s_or_b64 exec, exec, s[0:1]
	v_ashrrev_i32_e32 v3, 31, v2
	v_or_b32_e32 v3, 0x80000000, v3
	v_xor_b32_e32 v3, v2, v3
	s_mov_b32 s98, 0
	s_or_b32 s100, s98, 0x80000000
	v_cmp_le_u32_e32 vcc, s100, v3
	s_and_b64 s[0:1], vcc, s[8:9]
	s_bcnt1_i32_b64 s101, s[0:1]
	s_cmp_ge_u32 s101, 13
	s_cselect_b32 s98, s100, s98
	s_or_b32 s100, s98, 0x40000000
	v_cmp_le_u32_e32 vcc, s100, v3
	s_and_b64 s[0:1], vcc, s[8:9]
	s_bcnt1_i32_b64 s101, s[0:1]
	s_cmp_ge_u32 s101, 13
	s_cselect_b32 s98, s100, s98
	s_or_b32 s100, s98, 0x20000000
	v_cmp_le_u32_e32 vcc, s100, v3
	s_and_b64 s[0:1], vcc, s[8:9]
	s_bcnt1_i32_b64 s101, s[0:1]
	s_cmp_ge_u32 s101, 13
	s_cselect_b32 s98, s100, s98
	s_or_b32 s100, s98, 0x10000000
	v_cmp_le_u32_e32 vcc, s100, v3
	s_and_b64 s[0:1], vcc, s[8:9]
	s_bcnt1_i32_b64 s101, s[0:1]
	s_cmp_ge_u32 s101, 13
	s_cselect_b32 s98, s100, s98
	s_or_b32 s100, s98, 0x8000000
	v_cmp_le_u32_e32 vcc, s100, v3
	s_and_b64 s[0:1], vcc, s[8:9]
	s_bcnt1_i32_b64 s101, s[0:1]
	s_cmp_ge_u32 s101, 13
	s_cselect_b32 s98, s100, s98
	s_or_b32 s100, s98, 0x4000000
	v_cmp_le_u32_e32 vcc, s100, v3
	s_and_b64 s[0:1], vcc, s[8:9]
	s_bcnt1_i32_b64 s101, s[0:1]
	s_cmp_ge_u32 s101, 13
	s_cselect_b32 s98, s100, s98
	s_or_b32 s100, s98, 0x2000000
	v_cmp_le_u32_e32 vcc, s100, v3
	s_and_b64 s[0:1], vcc, s[8:9]
	s_bcnt1_i32_b64 s101, s[0:1]
	s_cmp_ge_u32 s101, 13
	s_cselect_b32 s98, s100, s98
	s_or_b32 s100, s98, 0x1000000
	v_cmp_le_u32_e32 vcc, s100, v3
	s_and_b64 s[0:1], vcc, s[8:9]
	s_bcnt1_i32_b64 s101, s[0:1]
	s_cmp_ge_u32 s101, 13
	s_cselect_b32 s98, s100, s98
	s_or_b32 s100, s98, 0x800000
	v_cmp_le_u32_e32 vcc, s100, v3
	s_and_b64 s[0:1], vcc, s[8:9]
	s_bcnt1_i32_b64 s101, s[0:1]
	s_cmp_ge_u32 s101, 13
	s_cselect_b32 s98, s100, s98
	s_or_b32 s100, s98, 0x400000
	v_cmp_le_u32_e32 vcc, s100, v3
	s_and_b64 s[0:1], vcc, s[8:9]
	s_bcnt1_i32_b64 s101, s[0:1]
	s_cmp_ge_u32 s101, 13
	s_cselect_b32 s98, s100, s98
	s_or_b32 s100, s98, 0x200000
	v_cmp_le_u32_e32 vcc, s100, v3
	s_and_b64 s[0:1], vcc, s[8:9]
	s_bcnt1_i32_b64 s101, s[0:1]
	s_cmp_ge_u32 s101, 13
	s_cselect_b32 s98, s100, s98
	s_or_b32 s100, s98, 0x100000
	v_cmp_le_u32_e32 vcc, s100, v3
	s_and_b64 s[0:1], vcc, s[8:9]
	s_bcnt1_i32_b64 s101, s[0:1]
	s_cmp_ge_u32 s101, 13
	s_cselect_b32 s98, s100, s98
	s_or_b32 s100, s98, 0x80000
	v_cmp_le_u32_e32 vcc, s100, v3
	s_and_b64 s[0:1], vcc, s[8:9]
	s_bcnt1_i32_b64 s101, s[0:1]
	s_cmp_ge_u32 s101, 13
	s_cselect_b32 s98, s100, s98
	s_or_b32 s100, s98, 0x40000
	v_cmp_le_u32_e32 vcc, s100, v3
	s_and_b64 s[0:1], vcc, s[8:9]
	s_bcnt1_i32_b64 s101, s[0:1]
	s_cmp_ge_u32 s101, 13
	s_cselect_b32 s98, s100, s98
	s_or_b32 s100, s98, 0x20000
	v_cmp_le_u32_e32 vcc, s100, v3
	s_and_b64 s[0:1], vcc, s[8:9]
	s_bcnt1_i32_b64 s101, s[0:1]
	s_cmp_ge_u32 s101, 13
	s_cselect_b32 s98, s100, s98
	s_or_b32 s100, s98, 0x10000
	v_cmp_le_u32_e32 vcc, s100, v3
	s_and_b64 s[0:1], vcc, s[8:9]
	s_bcnt1_i32_b64 s101, s[0:1]
	s_cmp_ge_u32 s101, 13
	s_cselect_b32 s98, s100, s98
	s_or_b32 s100, s98, 0x8000
	v_cmp_le_u32_e32 vcc, s100, v3
	s_and_b64 s[0:1], vcc, s[8:9]
	s_bcnt1_i32_b64 s101, s[0:1]
	s_cmp_ge_u32 s101, 13
	s_cselect_b32 s98, s100, s98
	s_or_b32 s100, s98, 0x4000
	v_cmp_le_u32_e32 vcc, s100, v3
	s_and_b64 s[0:1], vcc, s[8:9]
	s_bcnt1_i32_b64 s101, s[0:1]
	s_cmp_ge_u32 s101, 13
	s_cselect_b32 s98, s100, s98
	s_or_b32 s100, s98, 0x2000
	v_cmp_le_u32_e32 vcc, s100, v3
	s_and_b64 s[0:1], vcc, s[8:9]
	s_bcnt1_i32_b64 s101, s[0:1]
	s_cmp_ge_u32 s101, 13
	s_cselect_b32 s98, s100, s98
	s_or_b32 s100, s98, 0x1000
	v_cmp_le_u32_e32 vcc, s100, v3
	s_and_b64 s[0:1], vcc, s[8:9]
	s_bcnt1_i32_b64 s101, s[0:1]
	s_cmp_ge_u32 s101, 13
	s_cselect_b32 s98, s100, s98
	s_or_b32 s100, s98, 0x800
	v_cmp_le_u32_e32 vcc, s100, v3
	s_and_b64 s[0:1], vcc, s[8:9]
	s_bcnt1_i32_b64 s101, s[0:1]
	s_cmp_ge_u32 s101, 13
	s_cselect_b32 s98, s100, s98
	s_or_b32 s100, s98, 0x400
	v_cmp_le_u32_e32 vcc, s100, v3
	s_and_b64 s[0:1], vcc, s[8:9]
	s_bcnt1_i32_b64 s101, s[0:1]
	s_cmp_ge_u32 s101, 13
	s_cselect_b32 s98, s100, s98
	s_or_b32 s100, s98, 0x200
	v_cmp_le_u32_e32 vcc, s100, v3
	s_and_b64 s[0:1], vcc, s[8:9]
	s_bcnt1_i32_b64 s101, s[0:1]
	s_cmp_ge_u32 s101, 13
	s_cselect_b32 s98, s100, s98
	s_or_b32 s100, s98, 0x100
	v_cmp_le_u32_e32 vcc, s100, v3
	s_and_b64 s[0:1], vcc, s[8:9]
	s_bcnt1_i32_b64 s101, s[0:1]
	s_cmp_ge_u32 s101, 13
	s_cselect_b32 s98, s100, s98
	s_or_b32 s100, s98, 0x80
	v_cmp_le_u32_e32 vcc, s100, v3
	s_and_b64 s[0:1], vcc, s[8:9]
	s_bcnt1_i32_b64 s101, s[0:1]
	s_cmp_ge_u32 s101, 13
	s_cselect_b32 s98, s100, s98
	s_or_b32 s100, s98, 64
	v_cmp_le_u32_e32 vcc, s100, v3
	s_and_b64 s[0:1], vcc, s[8:9]
	s_bcnt1_i32_b64 s101, s[0:1]
	s_cmp_ge_u32 s101, 13
	s_cselect_b32 s98, s100, s98
	s_or_b32 s100, s98, 32
	v_cmp_le_u32_e32 vcc, s100, v3
	s_and_b64 s[0:1], vcc, s[8:9]
	s_bcnt1_i32_b64 s101, s[0:1]
	s_cmp_ge_u32 s101, 13
	s_cselect_b32 s98, s100, s98
	s_or_b32 s100, s98, 16
	v_cmp_le_u32_e32 vcc, s100, v3
	s_and_b64 s[0:1], vcc, s[8:9]
	s_bcnt1_i32_b64 s101, s[0:1]
	s_cmp_ge_u32 s101, 13
	s_cselect_b32 s98, s100, s98
	s_or_b32 s100, s98, 8
	v_cmp_le_u32_e32 vcc, s100, v3
	s_and_b64 s[0:1], vcc, s[8:9]
	s_bcnt1_i32_b64 s101, s[0:1]
	s_cmp_ge_u32 s101, 13
	s_cselect_b32 s98, s100, s98
	s_or_b32 s100, s98, 4
	v_cmp_le_u32_e32 vcc, s100, v3
	s_and_b64 s[0:1], vcc, s[8:9]
	s_bcnt1_i32_b64 s101, s[0:1]
	s_cmp_ge_u32 s101, 13
	s_cselect_b32 s98, s100, s98
	s_or_b32 s100, s98, 2
	v_cmp_le_u32_e32 vcc, s100, v3
	s_and_b64 s[0:1], vcc, s[8:9]
	s_bcnt1_i32_b64 s101, s[0:1]
	s_cmp_ge_u32 s101, 13
	s_cselect_b32 s98, s100, s98
	s_or_b32 s100, s98, 1
	v_cmp_le_u32_e32 vcc, s100, v3
	s_and_b64 s[0:1], vcc, s[8:9]
	s_bcnt1_i32_b64 s101, s[0:1]
	s_cmp_ge_u32 s101, 13
	s_cselect_b32 s98, s100, s98
	v_cmp_lt_u32_e32 vcc, s98, v3
	s_and_b64 s[0:1], vcc, s[8:9]
	s_bcnt1_i32_b64 s101, s[0:1]
	s_sub_i32 s99, 13, s101
	v_cmp_eq_u32_e32 vcc, s98, v3
	s_and_b64 vcc, vcc, s[8:9]
	s_nop 1
	v_mbcnt_lo_u32_b32 v4, vcc_lo, 0
	v_mbcnt_hi_u32_b32 v4, vcc_hi, v4
	v_cmp_gt_u32_e64 s[100:101], s99, v4
	s_and_b64 vcc, vcc, s[100:101]
	s_or_b64 vcc, vcc, s[0:1]
	s_or_b64 s[24:25], s[10:11], vcc
	s_or_b32 s24, s24, 1

; __device__ __forceinline__ float rdlane(float v, int l) { return __int_as_float(__builtin_amdgcn_readlane(__float_as_int(v), l)); }
; __device__ __forceinline__ void nsa_unit(Frame& F, int b, int g, int c) {
;     ...
;         for (int tt = 0; tt < 8; ++tt) {
;             const int tl = 8 * w + tt; unsigned long long mk;
;             if (c >= 16) {
;                 const bool cand = (lane >= 1) && (lane <= c - 2);
;                 const float v = cand ? impG[tl * 64 + lane] + impL[tl * 64 + lane] : -__builtin_inff();
;                 int rank = 0;
;                 for (int i = 0; i < 64; ++i) { const float vi = rdlane(v, i); rank += ((vi > v) || (vi == v && i < lane)) ? 1 : 0; }
;                 mk = __ballot(cand && rank < 13) | 1ull | (1ull << c) | (1ull << (c - 1));
;             } else mk = (2ull << c) - 1ull;
;             if (lane == 0) selm[tl] = mk;
;             wuni |= mk;
.LBB0_947:
	s_or_b64 exec, exec, s[0:1]
	v_ashrrev_i32_e32 v3, 31, v2
	v_or_b32_e32 v3, 0x80000000, v3
	v_xor_b32_e32 v3, v2, v3
	s_mov_b32 s98, 0
	s_or_b32 s100, s98, 0x80000000
	v_cmp_le_u32_e32 vcc, s100, v3
	s_and_b64 s[0:1], vcc, s[8:9]
	s_bcnt1_i32_b64 s101, s[0:1]
	s_cmp_ge_u32 s101, 13
	s_cselect_b32 s98, s100, s98
	s_or_b32 s100, s98, 0x40000000
	v_cmp_le_u32_e32 vcc, s100, v3
	s_and_b64 s[0:1], vcc, s[8:9]
	s_bcnt1_i32_b64 s101, s[0:1]
	s_cmp_ge_u32 s101, 13
	s_cselect_b32 s98, s100, s98
	s_or_b32 s100, s98, 0x20000000
	v_cmp_le_u32_e32 vcc, s100, v3
	s_and_b64 s[0:1], vcc, s[8:9]
	s_bcnt1_i32_b64 s101, s[0:1]
	s_cmp_ge_u32 s101, 13
	s_cselect_b32 s98, s100, s98
	s_or_b32 s100, s98, 0x10000000
	v_cmp_le_u32_e32 vcc, s100, v3
	s_and_b64 s[0:1], vcc, s[8:9]
	s_bcnt1_i32_b64 s101, s[0:1]
	s_cmp_ge_u32 s101, 13
	s_cselect_b32 s98, s100, s98
	s_or_b32 s100, s98, 0x8000000
	v_cmp_le_u32_e32 vcc, s100, v3
	s_and_b64 s[0:1], vcc, s[8:9]
	s_bcnt1_i32_b64 s101, s[0:1]
	s_cmp_ge_u32 s101, 13
	s_cselect_b32 s98, s100, s98
	s_or_b32 s100, s98, 0x4000000
	v_cmp_le_u32_e32 vcc, s100, v3
	s_and_b64 s[0:1], vcc, s[8:9]
	s_bcnt1_i32_b64 s101, s[0:1]
	s_cmp_ge_u32 s101, 13
	s_cselect_b32 s98, s100, s98
	s_or_b32 s100, s98, 0x2000000
	v_cmp_le_u32_e32 vcc, s100, v3
	s_and_b64 s[0:1], vcc, s[8:9]
	s_bcnt1_i32_b64 s101, s[0:1]
	s_cmp_ge_u32 s101, 13
	s_cselect_b32 s98, s100, s98
	s_or_b32 s100, s98, 0x1000000
	v_cmp_le_u32_e32 vcc, s100, v3
	s_and_b64 s[0:1], vcc, s[8:9]
	s_bcnt1_i32_b64 s101, s[0:1]
	s_cmp_ge_u32 s101, 13
	s_cselect_b32 s98, s100, s98
	s_or_b32 s100, s98, 0x800000
	v_cmp_le_u32_e32 vcc, s100, v3
	s_and_b64 s[0:1], vcc, s[8:9]
	s_bcnt1_i32_b64 s101, s[0:1]
	s_cmp_ge_u32 s101, 13
	s_cselect_b32 s98, s100, s98
	s_or_b32 s100, s98, 0x400000
	v_cmp_le_u32_e32 vcc, s100, v3
	s_and_b64 s[0:1], vcc, s[8:9]
	s_bcnt1_i32_b64 s101, s[0:1]
	s_cmp_ge_u32 s101, 13
	s_cselect_b32 s98, s100, s98
	s_or_b32 s100, s98, 0x200000
	v_cmp_le_u32_e32 vcc, s100, v3
	s_and_b64 s[0:1], vcc, s[8:9]
	s_bcnt1_i32_b64 s101, s[0:1]
	s_cmp_ge_u32 s101, 13
	s_cselect_b32 s98, s100, s98
	s_or_b32 s100, s98, 0x100000
	v_cmp_le_u32_e32 vcc, s100, v3
	s_and_b64 s[0:1], vcc, s[8:9]
	s_bcnt1_i32_b64 s101, s[0:1]
	s_cmp_ge_u32 s101, 13
	s_cselect_b32 s98, s100, s98
	s_or_b32 s100, s98, 0x80000
	v_cmp_le_u32_e32 vcc, s100, v3
	s_and_b64 s[0:1], vcc, s[8:9]
	s_bcnt1_i32_b64 s101, s[0:1]
	s_cmp_ge_u32 s101, 13
	s_cselect_b32 s98, s100, s98
	s_or_b32 s100, s98, 0x40000
	v_cmp_le_u32_e32 vcc, s100, v3
	s_and_b64 s[0:1], vcc, s[8:9]
	s_bcnt1_i32_b64 s101, s[0:1]
	s_cmp_ge_u32 s101, 13
	s_cselect_b32 s98, s100, s98
	s_or_b32 s100, s98, 0x20000
	v_cmp_le_u32_e32 vcc, s100, v3
	s_and_b64 s[0:1], vcc, s[8:9]
	s_bcnt1_i32_b64 s101, s[0:1]
	s_cmp_ge_u32 s101, 13
	s_cselect_b32 s98, s100, s98
	s_or_b32 s100, s98, 0x10000
	v_cmp_le_u32_e32 vcc, s100, v3
	s_and_b64 s[0:1], vcc, s[8:9]
	s_bcnt1_i32_b64 s101, s[0:1]
	s_cmp_ge_u32 s101, 13
	s_cselect_b32 s98, s100, s98
	s_or_b32 s100, s98, 0x8000
	v_cmp_le_u32_e32 vcc, s100, v3
	s_and_b64 s[0:1], vcc, s[8:9]
	s_bcnt1_i32_b64 s101, s[0:1]
	s_cmp_ge_u32 s101, 13
	s_cselect_b32 s98, s100, s98
	s_or_b32 s100, s98, 0x4000
	v_cmp_le_u32_e32 vcc, s100, v3
	s_and_b64 s[0:1], vcc, s[8:9]
	s_bcnt1_i32_b64 s101, s[0:1]
	s_cmp_ge_u32 s101, 13
	s_cselect_b32 s98, s100, s98
	s_or_b32 s100, s98, 0x2000
	v_cmp_le_u32_e32 vcc, s100, v3
	s_and_b64 s[0:1], vcc, s[8:9]
	s_bcnt1_i32_b64 s101, s[0:1]
	s_cmp_ge_u32 s101, 13
	s_cselect_b32 s98, s100, s98
	s_or_b32 s100, s98, 0x1000
	v_cmp_le_u32_e32 vcc, s100, v3
	s_and_b64 s[0:1], vcc, s[8:9]
	s_bcnt1_i32_b64 s101, s[0:1]
	s_cmp_ge_u32 s101, 13
	s_cselect_b32 s98, s100, s98
	s_or_b32 s100, s98, 0x800
	v_cmp_le_u32_e32 vcc, s100, v3
	s_and_b64 s[0:1], vcc, s[8:9]
	s_bcnt1_i32_b64 s101, s[0:1]
	s_cmp_ge_u32 s101, 13
	s_cselect_b32 s98, s100, s98
	s_or_b32 s100, s98, 0x400
	v_cmp_le_u32_e32 vcc, s100, v3
	s_and_b64 s[0:1], vcc, s[8:9]
	s_bcnt1_i32_b64 s101, s[0:1]
	s_cmp_ge_u32 s101, 13
	s_cselect_b32 s98, s100, s98
	s_or_b32 s100, s98, 0x200
	v_cmp_le_u32_e32 vcc, s100, v3
	s_and_b64 s[0:1], vcc, s[8:9]
	s_bcnt1_i32_b64 s101, s[0:1]
	s_cmp_ge_u32 s101, 13
	s_cselect_b32 s98, s100, s98
	s_or_b32 s100, s98, 0x100
	v_cmp_le_u32_e32 vcc, s100, v3
	s_and_b64 s[0:1], vcc, s[8:9]
	s_bcnt1_i32_b64 s101, s[0:1]
	s_cmp_ge_u32 s101, 13
	s_cselect_b32 s98, s100, s98
	s_or_b32 s100, s98, 0x80
	v_cmp_le_u32_e32 vcc, s100, v3
	s_and_b64 s[0:1], vcc, s[8:9]
	s_bcnt1_i32_b64 s101, s[0:1]
	s_cmp_ge_u32 s101, 13
	s_cselect_b32 s98, s100, s98
	s_or_b32 s100, s98, 64
	v_cmp_le_u32_e32 vcc, s100, v3
	s_and_b64 s[0:1], vcc, s[8:9]
	s_bcnt1_i32_b64 s101, s[0:1]
	s_cmp_ge_u32 s101, 13
	s_cselect_b32 s98, s100, s98
	s_or_b32 s100, s98, 32
	v_cmp_le_u32_e32 vcc, s100, v3
	s_and_b64 s[0:1], vcc, s[8:9]
	s_bcnt1_i32_b64 s101, s[0:1]
	s_cmp_ge_u32 s101, 13
	s_cselect_b32 s98, s100, s98
	s_or_b32 s100, s98, 16
	v_cmp_le_u32_e32 vcc, s100, v3
	s_and_b64 s[0:1], vcc, s[8:9]
	s_bcnt1_i32_b64 s101, s[0:1]
	s_cmp_ge_u32 s101, 13
	s_cselect_b32 s98, s100, s98
	s_or_b32 s100, s98, 8
	v_cmp_le_u32_e32 vcc, s100, v3
	s_and_b64 s[0:1], vcc, s[8:9]
	s_bcnt1_i32_b64 s101, s[0:1]
	s_cmp_ge_u32 s101, 13
	s_cselect_b32 s98, s100, s98
	s_or_b32 s100, s98, 4
	v_cmp_le_u32_e32 vcc, s100, v3
	s_and_b64 s[0:1], vcc, s[8:9]
	s_bcnt1_i32_b64 s101, s[0:1]
	s_cmp_ge_u32 s101, 13
	s_cselect_b32 s98, s100, s98
	s_or_b32 s100, s98, 2
	v_cmp_le_u32_e32 vcc, s100, v3
	s_and_b64 s[0:1], vcc, s[8:9]
	s_bcnt1_i32_b64 s101, s[0:1]
	s_cmp_ge_u32 s101, 13
	s_cselect_b32 s98, s100, s98
	s_or_b32 s100, s98, 1
	v_cmp_le_u32_e32 vcc, s100, v3
	s_and_b64 s[0:1], vcc, s[8:9]
	s_bcnt1_i32_b64 s101, s[0:1]
	s_cmp_ge_u32 s101, 13
	s_cselect_b32 s98, s100, s98
	v_cmp_lt_u32_e32 vcc, s98, v3
	s_and_b64 s[0:1], vcc, s[8:9]
	s_bcnt1_i32_b64 s101, s[0:1]
	s_sub_i32 s99, 13, s101
	v_cmp_eq_u32_e32 vcc, s98, v3
	s_and_b64 vcc, vcc, s[8:9]
	s_nop 1
	v_mbcnt_lo_u32_b32 v4, vcc_lo, 0
	v_mbcnt_hi_u32_b32 v4, vcc_hi, v4
	v_cmp_gt_u32_e64 s[100:101], s99, v4
	s_and_b64 vcc, vcc, s[100:101]
	s_or_b64 vcc, vcc, s[0:1]
	s_or_b64 s[6:7], s[10:11], vcc
	s_or_b32 s6, s6, 1
	s_and_saveexec_b64 s[0:1], s[2:3]
	s_cbranch_execz .LBB0_916

; __device__ __forceinline__ float rdlane(float v, int l) { return __int_as_float(__builtin_amdgcn_readlane(__float_as_int(v), l)); }
; __device__ __forceinline__ void nsa_unit(Frame& F, int b, int g, int c) {
;     ...
;         for (int tt = 0; tt < 8; ++tt) {
;             const int tl = 8 * w + tt; unsigned long long mk;
;             if (c >= 16) {
;                 const bool cand = (lane >= 1) && (lane <= c - 2);
;                 const float v = cand ? impG[tl * 64 + lane] + impL[tl * 64 + lane] : -__builtin_inff();
;                 int rank = 0;
;                 for (int i = 0; i < 64; ++i) { const float vi = rdlane(v, i); rank += ((vi > v) || (vi == v && i < lane)) ? 1 : 0; }
;                 mk = __ballot(cand && rank < 13) | 1ull | (1ull << c) | (1ull << (c - 1));
;             } else mk = (2ull << c) - 1ull;
;             if (lane == 0) selm[tl] = mk;
;             wuni |= mk;
.LBB0_953:
	s_or_b64 exec, exec, s[0:1]
	v_ashrrev_i32_e32 v3, 31, v2
	v_or_b32_e32 v3, 0x80000000, v3
	v_xor_b32_e32 v3, v2, v3
	s_mov_b32 s98, 0
	s_or_b32 s100, s98, 0x80000000
	v_cmp_le_u32_e32 vcc, s100, v3
	s_and_b64 s[0:1], vcc, s[8:9]
	s_bcnt1_i32_b64 s101, s[0:1]
	s_cmp_ge_u32 s101, 13
	s_cselect_b32 s98, s100, s98
	s_or_b32 s100, s98, 0x40000000
	v_cmp_le_u32_e32 vcc, s100, v3
	s_and_b64 s[0:1], vcc, s[8:9]
	s_bcnt1_i32_b64 s101, s[0:1]
	s_cmp_ge_u32 s101, 13
	s_cselect_b32 s98, s100, s98
	s_or_b32 s100, s98, 0x20000000
	v_cmp_le_u32_e32 vcc, s100, v3
	s_and_b64 s[0:1], vcc, s[8:9]
	s_bcnt1_i32_b64 s101, s[0:1]
	s_cmp_ge_u32 s101, 13
	s_cselect_b32 s98, s100, s98
	s_or_b32 s100, s98, 0x10000000
	v_cmp_le_u32_e32 vcc, s100, v3
	s_and_b64 s[0:1], vcc, s[8:9]
	s_bcnt1_i32_b64 s101, s[0:1]
	s_cmp_ge_u32 s101, 13
	s_cselect_b32 s98, s100, s98
	s_or_b32 s100, s98, 0x8000000
	v_cmp_le_u32_e32 vcc, s100, v3
	s_and_b64 s[0:1], vcc, s[8:9]
	s_bcnt1_i32_b64 s101, s[0:1]
	s_cmp_ge_u32 s101, 13
	s_cselect_b32 s98, s100, s98
	s_or_b32 s100, s98, 0x4000000
	v_cmp_le_u32_e32 vcc, s100, v3
	s_and_b64 s[0:1], vcc, s[8:9]
	s_bcnt1_i32_b64 s101, s[0:1]
	s_cmp_ge_u32 s101, 13
	s_cselect_b32 s98, s100, s98
	s_or_b32 s100, s98, 0x2000000
	v_cmp_le_u32_e32 vcc, s100, v3
	s_and_b64 s[0:1], vcc, s[8:9]
	s_bcnt1_i32_b64 s101, s[0:1]
	s_cmp_ge_u32 s101, 13
	s_cselect_b32 s98, s100, s98
	s_or_b32 s100, s98, 0x1000000
	v_cmp_le_u32_e32 vcc, s100, v3
	s_and_b64 s[0:1], vcc, s[8:9]
	s_bcnt1_i32_b64 s101, s[0:1]
	s_cmp_ge_u32 s101, 13
	s_cselect_b32 s98, s100, s98
	s_or_b32 s100, s98, 0x800000
	v_cmp_le_u32_e32 vcc, s100, v3
	s_and_b64 s[0:1], vcc, s[8:9]
	s_bcnt1_i32_b64 s101, s[0:1]
	s_cmp_ge_u32 s101, 13
	s_cselect_b32 s98, s100, s98
	s_or_b32 s100, s98, 0x400000
	v_cmp_le_u32_e32 vcc, s100, v3
	s_and_b64 s[0:1], vcc, s[8:9]
	s_bcnt1_i32_b64 s101, s[0:1]
	s_cmp_ge_u32 s101, 13
	s_cselect_b32 s98, s100, s98
	s_or_b32 s100, s98, 0x200000
	v_cmp_le_u32_e32 vcc, s100, v3
	s_and_b64 s[0:1], vcc, s[8:9]
	s_bcnt1_i32_b64 s101, s[0:1]
	s_cmp_ge_u32 s101, 13
	s_cselect_b32 s98, s100, s98
	s_or_b32 s100, s98, 0x100000
	v_cmp_le_u32_e32 vcc, s100, v3
	s_and_b64 s[0:1], vcc, s[8:9]
	s_bcnt1_i32_b64 s101, s[0:1]
	s_cmp_ge_u32 s101, 13
	s_cselect_b32 s98, s100, s98
	s_or_b32 s100, s98, 0x80000
	v_cmp_le_u32_e32 vcc, s100, v3
	s_and_b64 s[0:1], vcc, s[8:9]
	s_bcnt1_i32_b64 s101, s[0:1]
	s_cmp_ge_u32 s101, 13
	s_cselect_b32 s98, s100, s98
	s_or_b32 s100, s98, 0x40000
	v_cmp_le_u32_e32 vcc, s100, v3
	s_and_b64 s[0:1], vcc, s[8:9]
	s_bcnt1_i32_b64 s101, s[0:1]
	s_cmp_ge_u32 s101, 13
	s_cselect_b32 s98, s100, s98
	s_or_b32 s100, s98, 0x20000
	v_cmp_le_u32_e32 vcc, s100, v3
	s_and_b64 s[0:1], vcc, s[8:9]
	s_bcnt1_i32_b64 s101, s[0:1]
	s_cmp_ge_u32 s101, 13
	s_cselect_b32 s98, s100, s98
	s_or_b32 s100, s98, 0x10000
	v_cmp_le_u32_e32 vcc, s100, v3
	s_and_b64 s[0:1], vcc, s[8:9]
	s_bcnt1_i32_b64 s101, s[0:1]
	s_cmp_ge_u32 s101, 13
	s_cselect_b32 s98, s100, s98
	s_or_b32 s100, s98, 0x8000
	v_cmp_le_u32_e32 vcc, s100, v3
	s_and_b64 s[0:1], vcc, s[8:9]
	s_bcnt1_i32_b64 s101, s[0:1]
	s_cmp_ge_u32 s101, 13
	s_cselect_b32 s98, s100, s98
	s_or_b32 s100, s98, 0x4000
	v_cmp_le_u32_e32 vcc, s100, v3
	s_and_b64 s[0:1], vcc, s[8:9]
	s_bcnt1_i32_b64 s101, s[0:1]
	s_cmp_ge_u32 s101, 13
	s_cselect_b32 s98, s100, s98
	s_or_b32 s100, s98, 0x2000
	v_cmp_le_u32_e32 vcc, s100, v3
	s_and_b64 s[0:1], vcc, s[8:9]
	s_bcnt1_i32_b64 s101, s[0:1]
	s_cmp_ge_u32 s101, 13
	s_cselect_b32 s98, s100, s98
	s_or_b32 s100, s98, 0x1000
	v_cmp_le_u32_e32 vcc, s100, v3
	s_and_b64 s[0:1], vcc, s[8:9]
	s_bcnt1_i32_b64 s101, s[0:1]
	s_cmp_ge_u32 s101, 13
	s_cselect_b32 s98, s100, s98
	s_or_b32 s100, s98, 0x800
	v_cmp_le_u32_e32 vcc, s100, v3
	s_and_b64 s[0:1], vcc, s[8:9]
	s_bcnt1_i32_b64 s101, s[0:1]
	s_cmp_ge_u32 s101, 13
	s_cselect_b32 s98, s100, s98
	s_or_b32 s100, s98, 0x400
	v_cmp_le_u32_e32 vcc, s100, v3
	s_and_b64 s[0:1], vcc, s[8:9]
	s_bcnt1_i32_b64 s101, s[0:1]
	s_cmp_ge_u32 s101, 13
	s_cselect_b32 s98, s100, s98
	s_or_b32 s100, s98, 0x200
	v_cmp_le_u32_e32 vcc, s100, v3
	s_and_b64 s[0:1], vcc, s[8:9]
	s_bcnt1_i32_b64 s101, s[0:1]
	s_cmp_ge_u32 s101, 13
	s_cselect_b32 s98, s100, s98
	s_or_b32 s100, s98, 0x100
	v_cmp_le_u32_e32 vcc, s100, v3
	s_and_b64 s[0:1], vcc, s[8:9]
	s_bcnt1_i32_b64 s101, s[0:1]
	s_cmp_ge_u32 s101, 13
	s_cselect_b32 s98, s100, s98
	s_or_b32 s100, s98, 0x80
	v_cmp_le_u32_e32 vcc, s100, v3
	s_and_b64 s[0:1], vcc, s[8:9]
	s_bcnt1_i32_b64 s101, s[0:1]
	s_cmp_ge_u32 s101, 13
	s_cselect_b32 s98, s100, s98
	s_or_b32 s100, s98, 64
	v_cmp_le_u32_e32 vcc, s100, v3
	s_and_b64 s[0:1], vcc, s[8:9]
	s_bcnt1_i32_b64 s101, s[0:1]
	s_cmp_ge_u32 s101, 13
	s_cselect_b32 s98, s100, s98
	s_or_b32 s100, s98, 32
	v_cmp_le_u32_e32 vcc, s100, v3
	s_and_b64 s[0:1], vcc, s[8:9]
	s_bcnt1_i32_b64 s101, s[0:1]
	s_cmp_ge_u32 s101, 13
	s_cselect_b32 s98, s100, s98
	s_or_b32 s100, s98, 16
	v_cmp_le_u32_e32 vcc, s100, v3
	s_and_b64 s[0:1], vcc, s[8:9]
	s_bcnt1_i32_b64 s101, s[0:1]
	s_cmp_ge_u32 s101, 13
	s_cselect_b32 s98, s100, s98
	s_or_b32 s100, s98, 8
	v_cmp_le_u32_e32 vcc, s100, v3
	s_and_b64 s[0:1], vcc, s[8:9]
	s_bcnt1_i32_b64 s101, s[0:1]
	s_cmp_ge_u32 s101, 13
	s_cselect_b32 s98, s100, s98
	s_or_b32 s100, s98, 4
	v_cmp_le_u32_e32 vcc, s100, v3
	s_and_b64 s[0:1], vcc, s[8:9]
	s_bcnt1_i32_b64 s101, s[0:1]
	s_cmp_ge_u32 s101, 13
	s_cselect_b32 s98, s100, s98
	s_or_b32 s100, s98, 2
	v_cmp_le_u32_e32 vcc, s100, v3
	s_and_b64 s[0:1], vcc, s[8:9]
	s_bcnt1_i32_b64 s101, s[0:1]
	s_cmp_ge_u32 s101, 13
	s_cselect_b32 s98, s100, s98
	s_or_b32 s100, s98, 1
	v_cmp_le_u32_e32 vcc, s100, v3
	s_and_b64 s[0:1], vcc, s[8:9]
	s_bcnt1_i32_b64 s101, s[0:1]
	s_cmp_ge_u32 s101, 13
	s_cselect_b32 s98, s100, s98
	v_cmp_lt_u32_e32 vcc, s98, v3
	s_and_b64 s[0:1], vcc, s[8:9]
	s_bcnt1_i32_b64 s101, s[0:1]
	s_sub_i32 s99, 13, s101
	v_cmp_eq_u32_e32 vcc, s98, v3
	s_and_b64 vcc, vcc, s[8:9]
	s_nop 1
	v_mbcnt_lo_u32_b32 v4, vcc_lo, 0
	v_mbcnt_hi_u32_b32 v4, vcc_hi, v4
	v_cmp_gt_u32_e64 s[100:101], s99, v4
	s_and_b64 vcc, vcc, s[100:101]
	s_or_b64 vcc, vcc, s[0:1]
	s_or_b64 s[12:13], s[10:11], vcc
	s_or_b32 s12, s12, 1
	s_and_saveexec_b64 s[0:1], s[2:3]
	s_cbranch_execnz .LBB0_918
	s_branch .LBB0_919
